# mode-3 (LN-residual f32) GEMM epilogue: next row group's loads issued before the current group's stores, waits are vmcnt(4) so stores are never waited for
# speedup vs baseline: 1.0161x; 1.0008x over previous
.LBB0_95:
	v_lshl_or_b32 v170, s82, 8, v176
	v_lshl_add_u32 v172, s81, 8, v174
	v_ashrrev_i32_e32 v171, 31, v170
	v_ashrrev_i32_e32 v173, 31, v172
	v_lshlrev_b64 v[48:49], 2, v[170:171]
	v_lshlrev_b64 v[178:179], 10, v[172:173]
	v_lshl_add_u64 v[52:53], s[50:51], 0, v[48:49]
	v_lshl_add_u64 v[60:61], s[52:53], 0, v[48:49]
	v_lshl_add_u64 v[178:179], v[178:179], 0, v[170:171]
	v_lshl_add_u64 v[180:181], v[172:173], 3, s[14:15]
	global_load_dwordx4 v[64:67], v[52:53], off offset:16
	global_load_dwordx4 v[72:75], v[52:53], off
	global_load_dwordx4 v[68:71], v[60:61], off offset:16
	global_load_dwordx4 v[76:79], v[60:61], off
	global_load_dwordx4 v[48:51], v[52:53], off offset:528
	global_load_dwordx4 v[56:59], v[52:53], off offset:512
	s_nop 0
	global_load_dwordx4 v[52:55], v[60:61], off offset:528
	s_nop 0
	global_load_dwordx4 v[60:63], v[60:61], off offset:512
	v_lshlrev_b64 v[198:199], 2, v[178:179]
	global_load_dwordx2 v[190:191], v[180:181], off
	v_lshl_add_u64 v[194:195], s[44:45], 0, v[198:199]
	global_load_dwordx4 v[178:181], v[194:195], off offset:16
	global_load_dwordx4 v[182:185], v[194:195], off
	global_load_dwordx4 v[186:189], v[194:195], off offset:528
	s_nop 0
	global_load_dwordx4 v[194:197], v[194:195], off offset:512
	s_mov_b64 s[28:29], -1
	s_and_b64 vcc, exec, s[40:41]
	s_waitcnt vmcnt(0)
	v_sub_f32_e32 v183, v183, v190
	v_sub_f32_e32 v182, v182, v190
	v_sub_f32_e32 v185, v185, v190
	v_sub_f32_e32 v184, v184, v190
	v_pk_mul_f32 v[184:185], v[190:191], v[184:185] op_sel:[1,0]
	v_pk_mul_f32 v[182:183], v[190:191], v[182:183] op_sel:[1,0]
	v_pk_fma_f32 v[184:185], v[74:75], v[184:185], v[78:79]
	v_pk_fma_f32 v[182:183], v[72:73], v[182:183], v[76:77]
	v_pk_fma_f32 v[158:159], v[184:185], s[22:23], v[158:159] op_sel_hi:[1,0,1]
	v_pk_fma_f32 v[156:157], v[182:183], s[22:23], v[156:157] op_sel_hi:[1,0,1]
	v_lshl_add_u64 v[182:183], s[46:47], 0, v[198:199]
	global_store_dwordx4 v[182:183], v[156:159], off
	s_nop 1
	v_sub_f32_e32 v157, v179, v190
	v_sub_f32_e32 v156, v178, v190
	v_sub_f32_e32 v159, v181, v190
	v_sub_f32_e32 v158, v180, v190
	v_pk_mul_f32 v[158:159], v[190:191], v[158:159] op_sel:[1,0]
	v_pk_mul_f32 v[156:157], v[190:191], v[156:157] op_sel:[1,0]
	v_pk_fma_f32 v[158:159], v[66:67], v[158:159], v[70:71]
	v_pk_fma_f32 v[156:157], v[64:65], v[156:157], v[68:69]
	v_pk_fma_f32 v[154:155], v[158:159], s[22:23], v[154:155] op_sel_hi:[1,0,1]
	v_pk_fma_f32 v[152:153], v[156:157], s[22:23], v[152:153] op_sel_hi:[1,0,1]
	global_store_dwordx4 v[182:183], v[152:155], off offset:16
	s_nop 1
	v_sub_f32_e32 v153, v195, v190
	v_sub_f32_e32 v152, v194, v190
	v_sub_f32_e32 v155, v197, v190
	v_sub_f32_e32 v154, v196, v190
	v_pk_mul_f32 v[154:155], v[190:191], v[154:155] op_sel:[1,0]
	v_pk_mul_f32 v[152:153], v[190:191], v[152:153] op_sel:[1,0]
	v_pk_fma_f32 v[154:155], v[58:59], v[154:155], v[62:63]
	v_pk_fma_f32 v[152:153], v[56:57], v[152:153], v[60:61]
	v_pk_fma_f32 v[150:151], v[154:155], s[22:23], v[150:151] op_sel_hi:[1,0,1]
	v_pk_fma_f32 v[148:149], v[152:153], s[22:23], v[148:149] op_sel_hi:[1,0,1]
	global_store_dwordx4 v[182:183], v[148:151], off offset:512
	s_nop 1
	v_sub_f32_e32 v149, v187, v190
	v_sub_f32_e32 v148, v186, v190
	v_sub_f32_e32 v151, v189, v190
	v_sub_f32_e32 v150, v188, v190
	v_pk_mul_f32 v[150:151], v[190:191], v[150:151] op_sel:[1,0]
	v_pk_mul_f32 v[148:149], v[190:191], v[148:149] op_sel:[1,0]
	v_pk_fma_f32 v[150:151], v[50:51], v[150:151], v[54:55]
	v_pk_fma_f32 v[148:149], v[48:49], v[148:149], v[52:53]
	v_pk_fma_f32 v[146:147], v[150:151], s[22:23], v[146:147] op_sel_hi:[1,0,1]
	v_pk_fma_f32 v[144:145], v[148:149], s[22:23], v[144:145] op_sel_hi:[1,0,1]
	global_store_dwordx4 v[182:183], v[144:147], off offset:528
	s_nop 1
	v_or_b32_e32 v144, 16, v172
	v_ashrrev_i32_e32 v145, 31, v144
	v_lshlrev_b64 v[146:147], 10, v[144:145]
	v_lshl_add_u64 v[146:147], v[146:147], 0, v[170:171]
	v_lshl_add_u64 v[144:145], v[144:145], 3, s[14:15]
	global_load_dwordx2 v[178:179], v[144:145], off
	v_lshlrev_b64 v[180:181], 2, v[146:147]
	v_lshl_add_u64 v[156:157], s[44:45], 0, v[180:181]
	global_load_dwordx4 v[144:147], v[156:157], off offset:16
	global_load_dwordx4 v[148:151], v[156:157], off
	global_load_dwordx4 v[152:155], v[156:157], off offset:528
	s_nop 0
	global_load_dwordx4 v[156:159], v[156:157], off offset:512
	s_waitcnt vmcnt(0)
	v_sub_f32_e32 v149, v149, v178
	v_sub_f32_e32 v148, v148, v178
	v_sub_f32_e32 v151, v151, v178
	v_sub_f32_e32 v150, v150, v178
	v_pk_mul_f32 v[150:151], v[178:179], v[150:151] op_sel:[1,0]
	v_pk_mul_f32 v[148:149], v[178:179], v[148:149] op_sel:[1,0]
	v_pk_fma_f32 v[150:151], v[74:75], v[150:151], v[78:79]
	v_pk_fma_f32 v[148:149], v[72:73], v[148:149], v[76:77]
	v_pk_fma_f32 v[142:143], v[150:151], s[22:23], v[142:143] op_sel_hi:[1,0,1]
	v_pk_fma_f32 v[140:141], v[148:149], s[22:23], v[140:141] op_sel_hi:[1,0,1]
	v_sub_f32_e32 v145, v145, v178
	v_sub_f32_e32 v144, v144, v178
	v_sub_f32_e32 v147, v147, v178
	v_sub_f32_e32 v146, v146, v178
	v_pk_mul_f32 v[146:147], v[178:179], v[146:147] op_sel:[1,0]
	v_pk_mul_f32 v[144:145], v[178:179], v[144:145] op_sel:[1,0]
	v_pk_fma_f32 v[146:147], v[66:67], v[146:147], v[70:71]
	v_pk_fma_f32 v[144:145], v[64:65], v[144:145], v[68:69]
	v_pk_fma_f32 v[138:139], v[146:147], s[22:23], v[138:139] op_sel_hi:[1,0,1]
	v_pk_fma_f32 v[136:137], v[144:145], s[22:23], v[136:137] op_sel_hi:[1,0,1]
	v_sub_f32_e32 v157, v157, v178
	v_sub_f32_e32 v156, v156, v178
	v_sub_f32_e32 v159, v159, v178
	v_sub_f32_e32 v158, v158, v178
	v_pk_mul_f32 v[158:159], v[178:179], v[158:159] op_sel:[1,0]
	v_pk_mul_f32 v[156:157], v[178:179], v[156:157] op_sel:[1,0]
	v_pk_fma_f32 v[158:159], v[58:59], v[158:159], v[62:63]
	v_pk_fma_f32 v[156:157], v[56:57], v[156:157], v[60:61]
	v_pk_fma_f32 v[134:135], v[158:159], s[22:23], v[134:135] op_sel_hi:[1,0,1]
	v_pk_fma_f32 v[132:133], v[156:157], s[22:23], v[132:133] op_sel_hi:[1,0,1]
	v_sub_f32_e32 v153, v153, v178
	v_sub_f32_e32 v152, v152, v178
	v_sub_f32_e32 v155, v155, v178
	v_sub_f32_e32 v154, v154, v178
	v_pk_mul_f32 v[154:155], v[178:179], v[154:155] op_sel:[1,0]
	v_pk_mul_f32 v[152:153], v[178:179], v[152:153] op_sel:[1,0]
	v_pk_fma_f32 v[154:155], v[50:51], v[154:155], v[54:55]
	v_pk_fma_f32 v[152:153], v[48:49], v[152:153], v[52:53]
	v_pk_fma_f32 v[130:131], v[154:155], s[22:23], v[130:131] op_sel_hi:[1,0,1]
	v_pk_fma_f32 v[128:129], v[152:153], s[22:23], v[128:129] op_sel_hi:[1,0,1]
	v_lshl_add_u64 v[248:249], s[46:47], 0, v[180:181]
	v_or_b32_e32 v206, 32, v172
	v_ashrrev_i32_e32 v207, 31, v206
	v_lshlrev_b64 v[208:209], 10, v[206:207]
	v_lshl_add_u64 v[208:209], v[208:209], 0, v[170:171]
	v_lshl_add_u64 v[206:207], v[206:207], 3, s[14:15]
	global_load_dwordx2 v[250:251], v[206:207], off
	v_lshlrev_b64 v[246:247], 2, v[208:209]
	v_lshl_add_u64 v[208:209], s[44:45], 0, v[246:247]
	global_load_dwordx4 v[144:147], v[208:209], off offset:16
	global_load_dwordx4 v[148:151], v[208:209], off
	global_load_dwordx4 v[152:155], v[208:209], off offset:528
	global_load_dwordx4 v[156:159], v[208:209], off offset:512
	global_store_dwordx4 v[248:249], v[140:143], off
	global_store_dwordx4 v[248:249], v[136:139], off offset:16
	global_store_dwordx4 v[248:249], v[132:135], off offset:512
	global_store_dwordx4 v[248:249], v[128:131], off offset:528
	s_waitcnt vmcnt(4)
	v_sub_f32_e32 v149, v149, v250
	v_sub_f32_e32 v148, v148, v250
	v_sub_f32_e32 v151, v151, v250
	v_sub_f32_e32 v150, v150, v250
	v_pk_mul_f32 v[150:151], v[250:251], v[150:151] op_sel:[1,0]
	v_pk_mul_f32 v[148:149], v[250:251], v[148:149] op_sel:[1,0]
	v_pk_fma_f32 v[150:151], v[74:75], v[150:151], v[78:79]
	v_pk_fma_f32 v[148:149], v[72:73], v[148:149], v[76:77]
	v_pk_fma_f32 v[126:127], v[150:151], s[22:23], v[126:127] op_sel_hi:[1,0,1]
	v_pk_fma_f32 v[124:125], v[148:149], s[22:23], v[124:125] op_sel_hi:[1,0,1]
	v_sub_f32_e32 v145, v145, v250
	v_sub_f32_e32 v144, v144, v250
	v_sub_f32_e32 v147, v147, v250
	v_sub_f32_e32 v146, v146, v250
	v_pk_mul_f32 v[146:147], v[250:251], v[146:147] op_sel:[1,0]
	v_pk_mul_f32 v[144:145], v[250:251], v[144:145] op_sel:[1,0]
	v_pk_fma_f32 v[146:147], v[66:67], v[146:147], v[70:71]
	v_pk_fma_f32 v[144:145], v[64:65], v[144:145], v[68:69]
	v_pk_fma_f32 v[122:123], v[146:147], s[22:23], v[122:123] op_sel_hi:[1,0,1]
	v_pk_fma_f32 v[120:121], v[144:145], s[22:23], v[120:121] op_sel_hi:[1,0,1]
	v_sub_f32_e32 v157, v157, v250
	v_sub_f32_e32 v156, v156, v250
	v_sub_f32_e32 v159, v159, v250
	v_sub_f32_e32 v158, v158, v250
	v_pk_mul_f32 v[158:159], v[250:251], v[158:159] op_sel:[1,0]
	v_pk_mul_f32 v[156:157], v[250:251], v[156:157] op_sel:[1,0]
	v_pk_fma_f32 v[158:159], v[58:59], v[158:159], v[62:63]
	v_pk_fma_f32 v[156:157], v[56:57], v[156:157], v[60:61]
	v_pk_fma_f32 v[118:119], v[158:159], s[22:23], v[118:119] op_sel_hi:[1,0,1]
	v_pk_fma_f32 v[116:117], v[156:157], s[22:23], v[116:117] op_sel_hi:[1,0,1]
	v_sub_f32_e32 v153, v153, v250
	v_sub_f32_e32 v152, v152, v250
	v_sub_f32_e32 v155, v155, v250
	v_sub_f32_e32 v154, v154, v250
	v_pk_mul_f32 v[154:155], v[250:251], v[154:155] op_sel:[1,0]
	v_pk_mul_f32 v[152:153], v[250:251], v[152:153] op_sel:[1,0]
	v_pk_fma_f32 v[154:155], v[50:51], v[154:155], v[54:55]
	v_pk_fma_f32 v[152:153], v[48:49], v[152:153], v[52:53]
	v_pk_fma_f32 v[114:115], v[154:155], s[22:23], v[114:115] op_sel_hi:[1,0,1]
	v_pk_fma_f32 v[112:113], v[152:153], s[22:23], v[112:113] op_sel_hi:[1,0,1]
	v_lshl_add_u64 v[248:249], s[46:47], 0, v[246:247]
	v_or_b32_e32 v206, 48, v172
	v_ashrrev_i32_e32 v207, 31, v206
	v_lshlrev_b64 v[208:209], 10, v[206:207]
	v_lshl_add_u64 v[208:209], v[208:209], 0, v[170:171]
	v_lshl_add_u64 v[206:207], v[206:207], 3, s[14:15]
	global_load_dwordx2 v[250:251], v[206:207], off
	v_lshlrev_b64 v[246:247], 2, v[208:209]
	v_lshl_add_u64 v[208:209], s[44:45], 0, v[246:247]
	global_load_dwordx4 v[144:147], v[208:209], off offset:16
	global_load_dwordx4 v[148:151], v[208:209], off
	global_load_dwordx4 v[152:155], v[208:209], off offset:528
	global_load_dwordx4 v[156:159], v[208:209], off offset:512
	global_store_dwordx4 v[248:249], v[124:127], off
	global_store_dwordx4 v[248:249], v[120:123], off offset:16
	global_store_dwordx4 v[248:249], v[116:119], off offset:512
	global_store_dwordx4 v[248:249], v[112:115], off offset:528
	s_waitcnt vmcnt(4)
	v_sub_f32_e32 v149, v149, v250
	v_sub_f32_e32 v148, v148, v250
	v_sub_f32_e32 v151, v151, v250
	v_sub_f32_e32 v150, v150, v250
	v_pk_mul_f32 v[150:151], v[250:251], v[150:151] op_sel:[1,0]
	v_pk_mul_f32 v[148:149], v[250:251], v[148:149] op_sel:[1,0]
	v_pk_fma_f32 v[150:151], v[74:75], v[150:151], v[78:79]
	v_pk_fma_f32 v[148:149], v[72:73], v[148:149], v[76:77]
	v_pk_fma_f32 v[110:111], v[150:151], s[22:23], v[110:111] op_sel_hi:[1,0,1]
	v_pk_fma_f32 v[108:109], v[148:149], s[22:23], v[108:109] op_sel_hi:[1,0,1]
	v_sub_f32_e32 v145, v145, v250
	v_sub_f32_e32 v144, v144, v250
	v_sub_f32_e32 v147, v147, v250
	v_sub_f32_e32 v146, v146, v250
	v_pk_mul_f32 v[146:147], v[250:251], v[146:147] op_sel:[1,0]
	v_pk_mul_f32 v[144:145], v[250:251], v[144:145] op_sel:[1,0]
	v_pk_fma_f32 v[146:147], v[66:67], v[146:147], v[70:71]
	v_pk_fma_f32 v[144:145], v[64:65], v[144:145], v[68:69]
	v_pk_fma_f32 v[106:107], v[146:147], s[22:23], v[106:107] op_sel_hi:[1,0,1]
	v_pk_fma_f32 v[104:105], v[144:145], s[22:23], v[104:105] op_sel_hi:[1,0,1]
	v_sub_f32_e32 v157, v157, v250
	v_sub_f32_e32 v156, v156, v250
	v_sub_f32_e32 v159, v159, v250
	v_sub_f32_e32 v158, v158, v250
	v_pk_mul_f32 v[158:159], v[250:251], v[158:159] op_sel:[1,0]
	v_pk_mul_f32 v[156:157], v[250:251], v[156:157] op_sel:[1,0]
	v_pk_fma_f32 v[158:159], v[58:59], v[158:159], v[62:63]
	v_pk_fma_f32 v[156:157], v[56:57], v[156:157], v[60:61]
	v_pk_fma_f32 v[102:103], v[158:159], s[22:23], v[102:103] op_sel_hi:[1,0,1]
	v_pk_fma_f32 v[100:101], v[156:157], s[22:23], v[100:101] op_sel_hi:[1,0,1]
	v_sub_f32_e32 v153, v153, v250
	v_sub_f32_e32 v152, v152, v250
	v_sub_f32_e32 v155, v155, v250
	v_sub_f32_e32 v154, v154, v250
	v_pk_mul_f32 v[154:155], v[250:251], v[154:155] op_sel:[1,0]
	v_pk_mul_f32 v[152:153], v[250:251], v[152:153] op_sel:[1,0]
	v_pk_fma_f32 v[154:155], v[50:51], v[154:155], v[54:55]
	v_pk_fma_f32 v[152:153], v[48:49], v[152:153], v[52:53]
	v_pk_fma_f32 v[98:99], v[154:155], s[22:23], v[98:99] op_sel_hi:[1,0,1]
	v_pk_fma_f32 v[96:97], v[152:153], s[22:23], v[96:97] op_sel_hi:[1,0,1]
	v_lshl_add_u64 v[248:249], s[46:47], 0, v[246:247]
	v_add_u32_e32 v206, 0x80, v172
	v_ashrrev_i32_e32 v207, 31, v206
	v_lshlrev_b64 v[208:209], 10, v[206:207]
	v_lshl_add_u64 v[208:209], v[208:209], 0, v[170:171]
	v_lshl_add_u64 v[206:207], v[206:207], 3, s[14:15]
	global_load_dwordx2 v[250:251], v[206:207], off
	v_lshlrev_b64 v[246:247], 2, v[208:209]
	v_lshl_add_u64 v[208:209], s[44:45], 0, v[246:247]
	global_load_dwordx4 v[144:147], v[208:209], off offset:16
	global_load_dwordx4 v[148:151], v[208:209], off
	global_load_dwordx4 v[152:155], v[208:209], off offset:528
	global_load_dwordx4 v[156:159], v[208:209], off offset:512
	global_store_dwordx4 v[248:249], v[108:111], off
	global_store_dwordx4 v[248:249], v[104:107], off offset:16
	global_store_dwordx4 v[248:249], v[100:103], off offset:512
	global_store_dwordx4 v[248:249], v[96:99], off offset:528
	s_waitcnt vmcnt(4)
	v_sub_f32_e32 v149, v149, v250
	v_sub_f32_e32 v148, v148, v250
	v_sub_f32_e32 v151, v151, v250
	v_sub_f32_e32 v150, v150, v250
	v_pk_mul_f32 v[150:151], v[250:251], v[150:151] op_sel:[1,0]
	v_pk_mul_f32 v[148:149], v[250:251], v[148:149] op_sel:[1,0]
	v_pk_fma_f32 v[150:151], v[74:75], v[150:151], v[78:79]
	v_pk_fma_f32 v[148:149], v[72:73], v[148:149], v[76:77]
	v_pk_fma_f32 v[94:95], v[150:151], s[22:23], v[94:95] op_sel_hi:[1,0,1]
	v_pk_fma_f32 v[92:93], v[148:149], s[22:23], v[92:93] op_sel_hi:[1,0,1]
	v_sub_f32_e32 v145, v145, v250
	v_sub_f32_e32 v144, v144, v250
	v_sub_f32_e32 v147, v147, v250
	v_sub_f32_e32 v146, v146, v250
	v_pk_mul_f32 v[146:147], v[250:251], v[146:147] op_sel:[1,0]
	v_pk_mul_f32 v[144:145], v[250:251], v[144:145] op_sel:[1,0]
	v_pk_fma_f32 v[146:147], v[66:67], v[146:147], v[70:71]
	v_pk_fma_f32 v[144:145], v[64:65], v[144:145], v[68:69]
	v_pk_fma_f32 v[90:91], v[146:147], s[22:23], v[90:91] op_sel_hi:[1,0,1]
	v_pk_fma_f32 v[88:89], v[144:145], s[22:23], v[88:89] op_sel_hi:[1,0,1]
	v_sub_f32_e32 v157, v157, v250
	v_sub_f32_e32 v156, v156, v250
	v_sub_f32_e32 v159, v159, v250
	v_sub_f32_e32 v158, v158, v250
	v_pk_mul_f32 v[158:159], v[250:251], v[158:159] op_sel:[1,0]
	v_pk_mul_f32 v[156:157], v[250:251], v[156:157] op_sel:[1,0]
	v_pk_fma_f32 v[158:159], v[58:59], v[158:159], v[62:63]
	v_pk_fma_f32 v[156:157], v[56:57], v[156:157], v[60:61]
	v_pk_fma_f32 v[86:87], v[158:159], s[22:23], v[86:87] op_sel_hi:[1,0,1]
	v_pk_fma_f32 v[84:85], v[156:157], s[22:23], v[84:85] op_sel_hi:[1,0,1]
	v_sub_f32_e32 v153, v153, v250
	v_sub_f32_e32 v152, v152, v250
	v_sub_f32_e32 v155, v155, v250
	v_sub_f32_e32 v154, v154, v250
	v_pk_mul_f32 v[154:155], v[250:251], v[154:155] op_sel:[1,0]
	v_pk_mul_f32 v[152:153], v[250:251], v[152:153] op_sel:[1,0]
	v_pk_fma_f32 v[154:155], v[50:51], v[154:155], v[54:55]
	v_pk_fma_f32 v[152:153], v[48:49], v[152:153], v[52:53]
	v_pk_fma_f32 v[82:83], v[154:155], s[22:23], v[82:83] op_sel_hi:[1,0,1]
	v_pk_fma_f32 v[80:81], v[152:153], s[22:23], v[80:81] op_sel_hi:[1,0,1]
	v_lshl_add_u64 v[248:249], s[46:47], 0, v[246:247]
	v_add_u32_e32 v206, 0x90, v172
	v_ashrrev_i32_e32 v207, 31, v206
	v_lshlrev_b64 v[208:209], 10, v[206:207]
	v_lshl_add_u64 v[208:209], v[208:209], 0, v[170:171]
	v_lshl_add_u64 v[206:207], v[206:207], 3, s[14:15]
	global_load_dwordx2 v[250:251], v[206:207], off
	v_lshlrev_b64 v[246:247], 2, v[208:209]
	v_lshl_add_u64 v[208:209], s[44:45], 0, v[246:247]
	global_load_dwordx4 v[144:147], v[208:209], off offset:16
	global_load_dwordx4 v[148:151], v[208:209], off
	global_load_dwordx4 v[152:155], v[208:209], off offset:528
	global_load_dwordx4 v[156:159], v[208:209], off offset:512
	global_store_dwordx4 v[248:249], v[92:95], off
	global_store_dwordx4 v[248:249], v[88:91], off offset:16
	global_store_dwordx4 v[248:249], v[84:87], off offset:512
	global_store_dwordx4 v[248:249], v[80:83], off offset:528
	s_waitcnt vmcnt(4)
	v_sub_f32_e32 v149, v149, v250
	v_sub_f32_e32 v148, v148, v250
	v_sub_f32_e32 v151, v151, v250
	v_sub_f32_e32 v150, v150, v250
	v_pk_mul_f32 v[150:151], v[250:251], v[150:151] op_sel:[1,0]
	v_pk_mul_f32 v[148:149], v[250:251], v[148:149] op_sel:[1,0]
	v_pk_fma_f32 v[150:151], v[74:75], v[150:151], v[78:79]
	v_pk_fma_f32 v[148:149], v[72:73], v[148:149], v[76:77]
	v_pk_fma_f32 v[46:47], v[150:151], s[22:23], v[46:47] op_sel_hi:[1,0,1]
	v_pk_fma_f32 v[44:45], v[148:149], s[22:23], v[44:45] op_sel_hi:[1,0,1]
	v_sub_f32_e32 v145, v145, v250
	v_sub_f32_e32 v144, v144, v250
	v_sub_f32_e32 v147, v147, v250
	v_sub_f32_e32 v146, v146, v250
	v_pk_mul_f32 v[146:147], v[250:251], v[146:147] op_sel:[1,0]
	v_pk_mul_f32 v[144:145], v[250:251], v[144:145] op_sel:[1,0]
	v_pk_fma_f32 v[146:147], v[66:67], v[146:147], v[70:71]
	v_pk_fma_f32 v[144:145], v[64:65], v[144:145], v[68:69]
	v_pk_fma_f32 v[42:43], v[146:147], s[22:23], v[42:43] op_sel_hi:[1,0,1]
	v_pk_fma_f32 v[40:41], v[144:145], s[22:23], v[40:41] op_sel_hi:[1,0,1]
	v_sub_f32_e32 v157, v157, v250
	v_sub_f32_e32 v156, v156, v250
	v_sub_f32_e32 v159, v159, v250
	v_sub_f32_e32 v158, v158, v250
	v_pk_mul_f32 v[158:159], v[250:251], v[158:159] op_sel:[1,0]
	v_pk_mul_f32 v[156:157], v[250:251], v[156:157] op_sel:[1,0]
	v_pk_fma_f32 v[158:159], v[58:59], v[158:159], v[62:63]
	v_pk_fma_f32 v[156:157], v[56:57], v[156:157], v[60:61]
	v_pk_fma_f32 v[38:39], v[158:159], s[22:23], v[38:39] op_sel_hi:[1,0,1]
	v_pk_fma_f32 v[36:37], v[156:157], s[22:23], v[36:37] op_sel_hi:[1,0,1]
	v_sub_f32_e32 v153, v153, v250
	v_sub_f32_e32 v152, v152, v250
	v_sub_f32_e32 v155, v155, v250
	v_sub_f32_e32 v154, v154, v250
	v_pk_mul_f32 v[154:155], v[250:251], v[154:155] op_sel:[1,0]
	v_pk_mul_f32 v[152:153], v[250:251], v[152:153] op_sel:[1,0]
	v_pk_fma_f32 v[154:155], v[50:51], v[154:155], v[54:55]
	v_pk_fma_f32 v[152:153], v[48:49], v[152:153], v[52:53]
	v_pk_fma_f32 v[34:35], v[154:155], s[22:23], v[34:35] op_sel_hi:[1,0,1]
	v_pk_fma_f32 v[32:33], v[152:153], s[22:23], v[32:33] op_sel_hi:[1,0,1]
	v_lshl_add_u64 v[248:249], s[46:47], 0, v[246:247]
	v_add_u32_e32 v206, 0xa0, v172
	v_ashrrev_i32_e32 v207, 31, v206
	v_lshlrev_b64 v[208:209], 10, v[206:207]
	v_lshl_add_u64 v[208:209], v[208:209], 0, v[170:171]
	v_lshl_add_u64 v[206:207], v[206:207], 3, s[14:15]
	global_load_dwordx2 v[250:251], v[206:207], off
	v_lshlrev_b64 v[246:247], 2, v[208:209]
	v_lshl_add_u64 v[208:209], s[44:45], 0, v[246:247]
	global_load_dwordx4 v[144:147], v[208:209], off offset:16
	global_load_dwordx4 v[148:151], v[208:209], off
	global_load_dwordx4 v[152:155], v[208:209], off offset:528
	global_load_dwordx4 v[156:159], v[208:209], off offset:512
	global_store_dwordx4 v[248:249], v[44:47], off
	global_store_dwordx4 v[248:249], v[40:43], off offset:16
	global_store_dwordx4 v[248:249], v[36:39], off offset:512
	global_store_dwordx4 v[248:249], v[32:35], off offset:528
	s_waitcnt vmcnt(4)
	v_sub_f32_e32 v149, v149, v250
	v_sub_f32_e32 v148, v148, v250
	v_sub_f32_e32 v151, v151, v250
	v_sub_f32_e32 v150, v150, v250
	v_pk_mul_f32 v[150:151], v[250:251], v[150:151] op_sel:[1,0]
	v_pk_mul_f32 v[148:149], v[250:251], v[148:149] op_sel:[1,0]
	v_pk_fma_f32 v[150:151], v[74:75], v[150:151], v[78:79]
	v_pk_fma_f32 v[148:149], v[72:73], v[148:149], v[76:77]
	v_pk_fma_f32 v[30:31], v[150:151], s[22:23], v[30:31] op_sel_hi:[1,0,1]
	v_pk_fma_f32 v[28:29], v[148:149], s[22:23], v[28:29] op_sel_hi:[1,0,1]
	v_sub_f32_e32 v145, v145, v250
	v_sub_f32_e32 v144, v144, v250
	v_sub_f32_e32 v147, v147, v250
	v_sub_f32_e32 v146, v146, v250
	v_pk_mul_f32 v[146:147], v[250:251], v[146:147] op_sel:[1,0]
	v_pk_mul_f32 v[144:145], v[250:251], v[144:145] op_sel:[1,0]
	v_pk_fma_f32 v[146:147], v[66:67], v[146:147], v[70:71]
	v_pk_fma_f32 v[144:145], v[64:65], v[144:145], v[68:69]
	v_pk_fma_f32 v[26:27], v[146:147], s[22:23], v[26:27] op_sel_hi:[1,0,1]
	v_pk_fma_f32 v[24:25], v[144:145], s[22:23], v[24:25] op_sel_hi:[1,0,1]
	v_sub_f32_e32 v157, v157, v250
	v_sub_f32_e32 v156, v156, v250
	v_sub_f32_e32 v159, v159, v250
	v_sub_f32_e32 v158, v158, v250
	v_pk_mul_f32 v[158:159], v[250:251], v[158:159] op_sel:[1,0]
	v_pk_mul_f32 v[156:157], v[250:251], v[156:157] op_sel:[1,0]
	v_pk_fma_f32 v[158:159], v[58:59], v[158:159], v[62:63]
	v_pk_fma_f32 v[156:157], v[56:57], v[156:157], v[60:61]
	v_pk_fma_f32 v[22:23], v[158:159], s[22:23], v[22:23] op_sel_hi:[1,0,1]
	v_pk_fma_f32 v[20:21], v[156:157], s[22:23], v[20:21] op_sel_hi:[1,0,1]
	v_sub_f32_e32 v153, v153, v250
	v_sub_f32_e32 v152, v152, v250
	v_sub_f32_e32 v155, v155, v250
	v_sub_f32_e32 v154, v154, v250
	v_pk_mul_f32 v[154:155], v[250:251], v[154:155] op_sel:[1,0]
	v_pk_mul_f32 v[152:153], v[250:251], v[152:153] op_sel:[1,0]
	v_pk_fma_f32 v[154:155], v[50:51], v[154:155], v[54:55]
	v_pk_fma_f32 v[152:153], v[48:49], v[152:153], v[52:53]
	v_pk_fma_f32 v[18:19], v[154:155], s[22:23], v[18:19] op_sel_hi:[1,0,1]
	v_pk_fma_f32 v[16:17], v[152:153], s[22:23], v[16:17] op_sel_hi:[1,0,1]
	v_lshl_add_u64 v[248:249], s[46:47], 0, v[246:247]
	v_add_u32_e32 v206, 0xb0, v172
	v_ashrrev_i32_e32 v207, 31, v206
	v_lshlrev_b64 v[208:209], 10, v[206:207]
	v_lshl_add_u64 v[208:209], v[208:209], 0, v[170:171]
	v_lshl_add_u64 v[206:207], v[206:207], 3, s[14:15]
	global_load_dwordx2 v[250:251], v[206:207], off
	v_lshlrev_b64 v[246:247], 2, v[208:209]
	v_lshl_add_u64 v[208:209], s[44:45], 0, v[246:247]
	global_load_dwordx4 v[144:147], v[208:209], off offset:16
	global_load_dwordx4 v[148:151], v[208:209], off
	global_load_dwordx4 v[152:155], v[208:209], off offset:528
	global_load_dwordx4 v[156:159], v[208:209], off offset:512
	global_store_dwordx4 v[248:249], v[28:31], off
	global_store_dwordx4 v[248:249], v[24:27], off offset:16
	global_store_dwordx4 v[248:249], v[20:23], off offset:512
	global_store_dwordx4 v[248:249], v[16:19], off offset:528
	s_waitcnt vmcnt(4)
	v_sub_f32_e32 v149, v149, v250
	v_sub_f32_e32 v148, v148, v250
	v_sub_f32_e32 v151, v151, v250
	v_sub_f32_e32 v150, v150, v250
	v_pk_mul_f32 v[150:151], v[250:251], v[150:151] op_sel:[1,0]
	v_pk_mul_f32 v[148:149], v[250:251], v[148:149] op_sel:[1,0]
	v_pk_fma_f32 v[150:151], v[74:75], v[150:151], v[78:79]
	v_pk_fma_f32 v[148:149], v[72:73], v[148:149], v[76:77]
	v_pk_fma_f32 v[14:15], v[150:151], s[22:23], v[14:15] op_sel_hi:[1,0,1]
	v_pk_fma_f32 v[12:13], v[148:149], s[22:23], v[12:13] op_sel_hi:[1,0,1]
	v_sub_f32_e32 v145, v145, v250
	v_sub_f32_e32 v144, v144, v250
	v_sub_f32_e32 v147, v147, v250
	v_sub_f32_e32 v146, v146, v250
	v_pk_mul_f32 v[146:147], v[250:251], v[146:147] op_sel:[1,0]
	v_pk_mul_f32 v[144:145], v[250:251], v[144:145] op_sel:[1,0]
	v_pk_fma_f32 v[146:147], v[66:67], v[146:147], v[70:71]
	v_pk_fma_f32 v[144:145], v[64:65], v[144:145], v[68:69]
	v_pk_fma_f32 v[10:11], v[146:147], s[22:23], v[10:11] op_sel_hi:[1,0,1]
	v_pk_fma_f32 v[8:9], v[144:145], s[22:23], v[8:9] op_sel_hi:[1,0,1]
	v_sub_f32_e32 v157, v157, v250
	v_sub_f32_e32 v156, v156, v250
	v_sub_f32_e32 v159, v159, v250
	v_sub_f32_e32 v158, v158, v250
	v_pk_mul_f32 v[158:159], v[250:251], v[158:159] op_sel:[1,0]
	v_pk_mul_f32 v[156:157], v[250:251], v[156:157] op_sel:[1,0]
	v_pk_fma_f32 v[158:159], v[58:59], v[158:159], v[62:63]
	v_pk_fma_f32 v[156:157], v[56:57], v[156:157], v[60:61]
	v_pk_fma_f32 v[6:7], v[158:159], s[22:23], v[6:7] op_sel_hi:[1,0,1]
	v_pk_fma_f32 v[4:5], v[156:157], s[22:23], v[4:5] op_sel_hi:[1,0,1]
	v_sub_f32_e32 v153, v153, v250
	v_sub_f32_e32 v152, v152, v250
	v_sub_f32_e32 v155, v155, v250
	v_sub_f32_e32 v154, v154, v250
	v_pk_mul_f32 v[154:155], v[250:251], v[154:155] op_sel:[1,0]
	v_pk_mul_f32 v[152:153], v[250:251], v[152:153] op_sel:[1,0]
	v_pk_fma_f32 v[154:155], v[50:51], v[154:155], v[54:55]
	v_pk_fma_f32 v[152:153], v[48:49], v[152:153], v[52:53]
	v_pk_fma_f32 v[2:3], v[154:155], s[22:23], v[2:3] op_sel_hi:[1,0,1]
	v_pk_fma_f32 v[0:1], v[152:153], s[22:23], v[0:1] op_sel_hi:[1,0,1]
	v_lshl_add_u64 v[248:249], s[46:47], 0, v[246:247]
	global_store_dwordx4 v[248:249], v[12:15], off
	global_store_dwordx4 v[248:249], v[8:11], off offset:16
	global_store_dwordx4 v[248:249], v[4:7], off offset:512
	global_store_dwordx4 v[248:249], v[0:3], off offset:528
	s_cbranch_vccnz .LBB0_83
	s_andn2_b64 vcc, exec, s[48:49]
	s_cbranch_vccnz .LBB0_82
	s_barrier
	s_branch .LBB0_82
